# sb attention dynamic queue sharded per XCD (8 counters) instead of one global counter
# speedup vs baseline: 1.0069x; 1.0069x over previous
; __device__ __forceinline__ void run_phase(const Args& a, const int ph, LAS unsigned char* lds, const int tid, const int rpt) {
;     ...
;                       for (;;) { int it0 = 0; if (lane == 0) it0 = (int)atomicAdd(qctr, 2u); it0 = nstat + __builtin_amdgcn_readfirstlane(it0); if (it0 >= 12 * 1024) break;
;                           for (int it = it0; it < it0 + 2; ++it) sb_item(hbuf, kmax2, mixed, vT, it, lane); } }
.LBB0_277:
	v_mov_b32_e32 v4, 0
	s_and_saveexec_b64 s[0:1], s[36:37]
	s_cbranch_execz .LBB0_281
	s_mov_b64 s[22:23], exec
	v_mbcnt_lo_u32_b32 v4, s22, 0
	v_mbcnt_hi_u32_b32 v4, s23, v4
	v_cmp_eq_u32_e32 vcc, 0, v4
	s_and_saveexec_b64 s[20:21], vcc
	s_cbranch_execz .LBB0_280
	s_bcnt1_i32_b64 s12, s[22:23]
	s_lshl_b32 s12, s12, 1
	v_readlane_b32 s22, v249, 7
	v_mov_b32_e32 v5, s12
	v_readlane_b32 s23, v249, 8
	v_readlane_b32 s98, v251, 8
	s_sub_u32 s98, s22, s98
	s_mul_i32 s98, s98, 3
	v_readlane_b32 s99, v251, 37
	s_lshl_b32 s99, s99, 5
	s_add_i32 s98, s98, s99
	s_add_u32 s22, s22, s98
	s_addc_u32 s23, s23, 0
	s_nop 4
	global_atomic_add v5, v33, v5, s[22:23] sc0

; __device__ __forceinline__ void run_phase(const Args& a, const int ph, LAS unsigned char* lds, const int tid, const int rpt) {
;     ...
;                       for (;;) { int it0 = 0; if (lane == 0) it0 = (int)atomicAdd(qctr, 2u); it0 = nstat + __builtin_amdgcn_readfirstlane(it0); if (it0 >= 12 * 1024) break;
;                           for (int it = it0; it < it0 + 2; ++it) sb_item(hbuf, kmax2, mixed, vT, it, lane); } }
.LBB0_281:
	s_or_b64 exec, exec, s[0:1]
	v_readfirstlane_b32 s12, v4
	s_cmp_ge_u32 s12, 0x200
	s_cselect_b32 s12, 0x10000, s12
	v_readlane_b32 s98, v251, 37
	s_lshl_b32 s98, s98, 9
	s_add_i32 s12, s12, s98
	v_readlane_b32 s0, v249, 54
	s_add_i32 s12, s12, s0
	s_mov_b64 s[0:1], -1
	s_cmpk_gt_i32 s12, 0x2fff
	s_mov_b32 s15, s12
	s_cbranch_scc0 .LBB0_283
	s_branch .LBB0_276
